# FFT phase: signal row kept in registers for the output gating instead of a second fetch
# speedup vs baseline: 1.0077x; 1.0003x over previous
.LBB0_1392:
	s_or_b64 exec, exec, s[0:1]
	v_lshl_add_u64 v[128:129], v[80:81], 2, s[4:5]
	global_load_dword v117, v[128:129], off
	s_lshl_b64 s[70:71], s[68:69], 13
	s_mov_b32 s0, 1
	s_waitcnt vmcnt(22)
	ds_write_b64 v33, v[4:5]
	v_mov_b64_e32 v[206:207], v[4:5]
	ds_write_b64 v146, v[182:183]
	s_waitcnt vmcnt(20)
	ds_write2st64_b64 v145, v[0:1], v[8:9] offset1:8
	s_waitcnt vmcnt(18)
	ds_write2st64_b64 v145, v[2:3], v[10:11] offset0:64 offset1:72
	ds_write_b64 v148, v[6:7]
	v_mov_b64_e32 v[208:209], v[6:7]
	ds_write_b64 v149, v[182:183]
	s_waitcnt vmcnt(16)
	ds_write_b64 v151, v[18:19]
	v_mov_b64_e32 v[210:211], v[18:19]
	ds_write_b64 v152, v[182:183]
	s_waitcnt vmcnt(14)
	ds_write2st64_b64 v145, v[12:13], v[22:23] offset0:16 offset1:24
	s_waitcnt vmcnt(12)
	ds_write2st64_b64 v145, v[16:17], v[14:15] offset0:80 offset1:88
	ds_write_b64 v154, v[20:21]
	v_mov_b64_e32 v[212:213], v[20:21]
	ds_write_b64 v155, v[182:183]
	s_waitcnt vmcnt(10)
	ds_write_b64 v156, v[30:31]
	v_mov_b64_e32 v[214:215], v[30:31]
	ds_write_b64 v157, v[182:183]
	s_waitcnt vmcnt(8)
	ds_write2st64_b64 v145, v[24:25], v[114:115] offset0:32 offset1:40
	s_waitcnt vmcnt(6)
	ds_write2st64_b64 v145, v[28:29], v[26:27] offset0:96 offset1:104
	ds_write_b64 v158, v[112:113]
	v_mov_b64_e32 v[216:217], v[112:113]
	ds_write_b64 v159, v[182:183]
	s_waitcnt vmcnt(4)
	ds_write_b64 v160, v[122:123]
	v_mov_b64_e32 v[218:219], v[122:123]
	ds_write_b64 v161, v[182:183]
	s_waitcnt vmcnt(2)
	ds_write2st64_b64 v145, v[120:121], v[126:127] offset0:48 offset1:56
	s_waitcnt vmcnt(1)
	ds_write_b64 v162, v[124:125]
	v_mov_b64_e32 v[220:221], v[124:125]
	ds_write_b64 v163, v[182:183]
	s_waitcnt vmcnt(0)
	ds_write2st64_b64 v145, v[118:119], v[116:117] offset0:112 offset1:120
	s_waitcnt lgkmcnt(0)
	s_barrier

.LBB0_1410:
	v_add_u32_e32 v28, 0x10000, v171
	s_waitcnt lgkmcnt(0)
	s_barrier
	ds_read_b128 v[0:3], v28
	ds_read_b128 v[4:7], v28 offset:8192
	ds_read_b128 v[8:11], v28 offset:16384
	ds_read_b128 v[12:15], v28 offset:24576
	ds_read_b128 v[16:19], v28 offset:32768
	ds_read_b128 v[20:23], v28 offset:40960
	ds_read_b128 v[24:27], v28 offset:49152
	ds_read_b128 v[28:31], v28 offset:57344
	s_waitcnt lgkmcnt(7)
	v_pk_add_f32 v[112:113], v[0:1], v[2:3]
	v_pk_add_f32 v[0:1], v[0:1], v[2:3] neg_lo:[0,1] neg_hi:[0,1]
	s_waitcnt lgkmcnt(6)
	v_pk_add_f32 v[2:3], v[4:5], v[6:7]
	s_waitcnt lgkmcnt(0)
	s_barrier
	ds_write2st64_b64 v33, v[112:113], v[2:3] offset1:8
	v_pk_add_f32 v[2:3], v[4:5], v[6:7] neg_lo:[0,1] neg_hi:[0,1]
	ds_write2st64_b64 v33, v[0:1], v[2:3] offset0:64 offset1:72
	v_pk_add_f32 v[0:1], v[8:9], v[10:11]
	v_pk_add_f32 v[4:5], v[12:13], v[14:15]
	v_pk_add_f32 v[2:3], v[8:9], v[10:11] neg_lo:[0,1] neg_hi:[0,1]
	ds_write2st64_b64 v33, v[0:1], v[4:5] offset0:16 offset1:24
	v_pk_add_f32 v[0:1], v[12:13], v[14:15] neg_lo:[0,1] neg_hi:[0,1]
	ds_write2st64_b64 v33, v[2:3], v[0:1] offset0:80 offset1:88
	v_pk_add_f32 v[0:1], v[16:17], v[18:19]
	v_pk_add_f32 v[4:5], v[20:21], v[22:23]
	v_pk_add_f32 v[2:3], v[16:17], v[18:19] neg_lo:[0,1] neg_hi:[0,1]
	ds_write2st64_b64 v33, v[0:1], v[4:5] offset0:32 offset1:40
	v_pk_add_f32 v[0:1], v[20:21], v[22:23] neg_lo:[0,1] neg_hi:[0,1]
	s_lshl_b64 s[20:21], s[70:71], 2
	ds_write2st64_b64 v33, v[2:3], v[0:1] offset0:96 offset1:104
	v_pk_add_f32 v[0:1], v[24:25], v[26:27]
	v_pk_add_f32 v[4:5], v[28:29], v[30:31]
	s_add_u32 s0, s46, s20
	v_pk_add_f32 v[2:3], v[24:25], v[26:27] neg_lo:[0,1] neg_hi:[0,1]
	ds_write2st64_b64 v33, v[0:1], v[4:5] offset0:48 offset1:56
	v_pk_add_f32 v[0:1], v[28:29], v[30:31] neg_lo:[0,1] neg_hi:[0,1]
	s_addc_u32 s1, s47, s21
	ds_write2st64_b64 v33, v[2:3], v[0:1] offset0:112 offset1:120
	v_lshl_add_u64 v[0:1], v[34:35], 2, s[0:1]
	v_lshl_add_u64 v[2:3], v[40:41], 2, s[0:1]
	v_lshl_add_u64 v[4:5], v[46:47], 2, s[0:1]
	v_lshl_add_u64 v[6:7], v[52:53], 2, s[0:1]
	v_lshl_add_u64 v[16:17], v[58:59], 2, s[0:1]
	v_lshl_add_u64 v[18:19], v[64:65], 2, s[0:1]
	v_lshl_add_u64 v[20:21], v[70:71], 2, s[0:1]
	v_lshl_add_u64 v[22:23], v[76:77], 2, s[0:1]
	s_waitcnt lgkmcnt(0)
	s_barrier
	v_mov_b64_e32 v[8:9], v[206:207]
	v_mov_b64_e32 v[10:11], v[208:209]
	v_mov_b64_e32 v[12:13], v[210:211]
	v_mov_b64_e32 v[14:15], v[212:213]
	s_nop 0
	global_load_dwordx2 v[0:1], v[0:1], off
	s_nop 0
	global_load_dwordx2 v[2:3], v[2:3], off
	s_nop 0
	global_load_dwordx2 v[4:5], v[4:5], off
	s_nop 0
	global_load_dwordx2 v[6:7], v[6:7], off
	s_nop 0
	v_mov_b64_e32 v[24:25], v[214:215]
	v_mov_b64_e32 v[26:27], v[216:217]
	v_mov_b64_e32 v[28:29], v[218:219]
	v_mov_b64_e32 v[30:31], v[220:221]
	s_nop 0
	global_load_dwordx2 v[16:17], v[16:17], off
	s_nop 0
	global_load_dwordx2 v[18:19], v[18:19], off
	s_nop 0
	global_load_dwordx2 v[20:21], v[20:21], off
	s_nop 0
	global_load_dwordx2 v[22:23], v[22:23], off
	s_movk_i32 s0, 0x400
